# GLA prep task prologue: gate-input tile load and first q/k group issued together with the gate-weight loads (one exposed latency per task instead of three)
# baseline (speedup 1.0000x reference)
; #define LAS __attribute__((address_space(3)))
; __device__ __forceinline__ void ph_prep(Frame& F, int e) {
;     ...
;     for (int task = blockIdx.x; task < NT; task += F.G) {
;         const int rc = task < 256 ? task : 256 + ((task - 256) >> 3), h = task < 256 ? F.wave : ((task - 256) & 7);
;         const bool active = task < 256 || F.wave == 0;
;         const bool lat = rc < 256;
;         const bf16* Prow0 = P + (size_t)rc * 64 * DINP;
;         col = 64 * h + dk;
; #pragma unroll
;         for (int i = 0; i < 16; ++i) wfb[i] = (pg8::f32x2){w2[i * 512 + col], w2[(16 + i) * 512 + col]} * 1.4426950408889634f;
;         bfb = (pg8::f32x2){bg[col], bg[512 + col]} * 1.4426950408889634f;
;         __syncthreads();
;         if (F.tid < 256) { const int row = F.tid >> 2, part = F.tid & 3; const v4u w = *(const v4u*)(Prow0 + (size_t)row * DINP + C_AB + 8 * part);
;             LAS float* d = ABf + row * 32 + 16 * (part & 1) + (part >> 1);
;             d[0] = bflo(w.x); d[2] = bfhi(w.x); d[4] = bflo(w.y); d[6] = bfhi(w.y); d[8] = bflo(w.z); d[10] = bfhi(w.z); d[12] = bflo(w.w); d[14] = bfhi(w.w); }
;         __syncthreads();
;         if (!active) continue;
;         const int prw = rc & 63;
;         float pf = 0.f, pbx = 0.f;
;         for (int t8 = 0; t8 < 64; t8 += 8) {
;             float qv[8], kv[8];
; #pragma unroll
;             for (int tt = 0; tt < 8; ++tt) { const bf16* prow = Prow0 + (size_t)(t8 + tt) * DINP; qv[tt] = bf2f(prow[C_QB + col]); kv[tt] = bf2f(prow[C_KB + col]); }
.LBB0_592:
	s_add_i32 s30, s21, 0xffffff00
	s_lshr_b32 s30, s30, 3
	s_addk_i32 s30, 0x100
	s_and_b32 s54, s21, 7
	s_cmpk_lt_i32 s21, 0x100
	s_cselect_b64 s[52:53], -1, 0
	s_and_b64 s[40:41], s[52:53], exec
	s_cselect_b32 s40, s8, s54
	v_lshl_or_b32 v42, s40, 6, v37
	v_ashrrev_i32_e32 v43, 31, v42
	v_lshlrev_b64 v[16:17], 2, v[42:43]
	v_lshl_add_u64 v[24:25], s[48:49], 0, v[16:17]
	v_add_co_u32_e32 v10, vcc, s33, v24
	v_add_u32_e32 v6, 0x2000, v42
	v_add_u32_e32 v8, 0x2200, v42
	v_addc_co_u32_e32 v11, vcc, 0, v25, vcc
	v_add_u32_e32 v12, 0x2400, v42
	v_ashrrev_i32_e32 v7, 31, v6
	v_ashrrev_i32_e32 v9, 31, v8
	v_add_co_u32_e32 v14, vcc, s81, v24
	v_ashrrev_i32_e32 v13, 31, v12
	v_lshl_add_u64 v[6:7], v[6:7], 2, s[48:49]
	v_lshl_add_u64 v[8:9], v[8:9], 2, s[48:49]
	v_addc_co_u32_e32 v15, vcc, 0, v25, vcc
	v_lshl_add_u64 v[12:13], v[12:13], 2, s[48:49]
	global_load_dword v4, v[24:25], off
	global_load_dword v5, v[6:7], off
	s_nop 0
	global_load_dword v6, v[24:25], off offset:2048
	global_load_dword v7, v[8:9], off
	v_add_u32_e32 v18, 0x2800, v42
	global_load_dword v8, v[14:15], off offset:-4096
	global_load_dword v9, v[12:13], off
	s_nop 0
	global_load_dword v10, v[10:11], off offset:2048
	v_add_u32_e32 v12, 0x2600, v42
	v_ashrrev_i32_e32 v13, 31, v12
	v_ashrrev_i32_e32 v19, 31, v18
	s_movk_i32 s3, 0x3000
	v_lshl_add_u64 v[12:13], v[12:13], 2, s[48:49]
	v_lshl_add_u64 v[18:19], v[18:19], 2, s[48:49]
	v_add_co_u32_e32 v20, vcc, s3, v24
	global_load_dword v11, v[12:13], off
	s_nop 0
	global_load_dword v12, v[14:15], off
	global_load_dword v13, v[18:19], off
	s_nop 0
	global_load_dword v14, v[14:15], off offset:2048
	v_add_u32_e32 v18, 0x2a00, v42
	v_addc_co_u32_e32 v21, vcc, 0, v25, vcc
	s_movk_i32 s15, 0x4000
	v_add_u32_e32 v22, 0x2c00, v42
	v_ashrrev_i32_e32 v19, 31, v18
	v_add_co_u32_e32 v26, vcc, s15, v24
	v_ashrrev_i32_e32 v23, 31, v22
	v_lshl_add_u64 v[18:19], v[18:19], 2, s[48:49]
	v_addc_co_u32_e32 v27, vcc, 0, v25, vcc
	v_lshl_add_u64 v[22:23], v[22:23], 2, s[48:49]
	global_load_dword v15, v[18:19], off
	v_add_u32_e32 v28, 0x3000, v42
	global_load_dword v18, v[26:27], off offset:-4096
	global_load_dword v19, v[22:23], off
	s_nop 0
	global_load_dword v20, v[20:21], off offset:2048
	v_add_u32_e32 v22, 0x2e00, v42
	v_ashrrev_i32_e32 v23, 31, v22
	v_ashrrev_i32_e32 v29, 31, v28
	v_lshl_add_u64 v[22:23], v[22:23], 2, s[48:49]
	v_lshl_add_u64 v[28:29], v[28:29], 2, s[48:49]
	v_add_co_u32_e32 v30, vcc, s85, v24
	global_load_dword v21, v[22:23], off
	s_nop 0
	global_load_dword v22, v[26:27], off
	global_load_dword v23, v[28:29], off
	s_nop 0
	global_load_dword v26, v[26:27], off offset:2048
	v_add_u32_e32 v28, 0x3200, v42
	v_addc_co_u32_e32 v31, vcc, 0, v25, vcc
	s_movk_i32 s40, 0x6000
	v_add_u32_e32 v32, 0x3400, v42
	v_ashrrev_i32_e32 v29, 31, v28
	v_add_co_u32_e32 v34, vcc, s40, v24
	v_ashrrev_i32_e32 v33, 31, v32
	v_lshl_add_u64 v[28:29], v[28:29], 2, s[48:49]
	v_addc_co_u32_e32 v35, vcc, 0, v25, vcc
	v_lshl_add_u64 v[32:33], v[32:33], 2, s[48:49]
	global_load_dword v27, v[28:29], off
	v_add_u32_e32 v44, 0x3800, v42
	global_load_dword v28, v[34:35], off offset:-4096
	global_load_dword v29, v[32:33], off
	s_nop 0
	global_load_dword v30, v[30:31], off offset:2048
	v_add_u32_e32 v32, 0x3600, v42
	v_ashrrev_i32_e32 v33, 31, v32
	v_ashrrev_i32_e32 v45, 31, v44
	v_lshl_add_u64 v[32:33], v[32:33], 2, s[48:49]
	v_lshl_add_u64 v[44:45], v[44:45], 2, s[48:49]
	global_load_dword v31, v[32:33], off
	s_nop 0
	global_load_dword v32, v[34:35], off
	global_load_dword v33, v[44:45], off
	s_nop 0
	global_load_dword v34, v[34:35], off offset:2048
	v_add_u32_e32 v44, 0x3a00, v42
	v_ashrrev_i32_e32 v45, 31, v44
	v_lshl_add_u64 v[44:45], v[44:45], 2, s[48:49]
	s_movk_i32 s3, 0x7000
	v_add_u32_e32 v46, 0x3c00, v42
	global_load_dword v35, v[44:45], off
	v_add_co_u32_e32 v44, vcc, s3, v24
	v_ashrrev_i32_e32 v47, 31, v46
	s_nop 0
	v_addc_co_u32_e32 v45, vcc, 0, v25, vcc
	v_lshl_add_u64 v[46:47], v[46:47], 2, s[48:49]
	global_load_dword v24, v[44:45], off
	global_load_dword v25, v[46:47], off
	global_load_dword v74, v[44:45], off offset:2048
	v_add_u32_e32 v44, 0x3e00, v42
	v_ashrrev_i32_e32 v45, 31, v44
	v_lshl_add_u64 v[44:45], v[44:45], 2, s[48:49]
	global_load_dword v75, v[44:45], off
	v_lshl_add_u64 v[44:45], s[42:43], 0, v[16:17]
	global_load_dword v16, v[44:45], off
	global_load_dword v17, v[44:45], off offset:2048
	s_cselect_b32 s54, s21, s30
	s_mul_hi_i32 s56, s54, 0xc8000
	s_mul_i32 s57, s54, 0xc8000
	s_add_u32 s40, s19, s57
	s_addc_u32 s41, s20, s56
	v_lshl_add_u64 v[78:79], v[42:43], 1, s[40:41]
	global_load_ushort v106, v[78:79], off
	global_load_ushort v107, v[78:79], off offset:1024
	v_add_co_u32_e32 v122, vcc, 0x3000, v78
	s_nop 1
	v_addc_co_u32_e32 v123, vcc, 0, v79, vcc
	global_load_ushort v108, v[122:123], off offset:512
	global_load_ushort v109, v[122:123], off offset:1536
	v_add_co_u32_e32 v124, vcc, 0x6000, v78
	s_nop 1
	v_addc_co_u32_e32 v125, vcc, 0, v79, vcc
	global_load_ushort v110, v[124:125], off offset:1024
	global_load_ushort v111, v[124:125], off offset:2048
	v_add_co_u32_e32 v126, vcc, 0x9000, v78
	s_nop 1
	v_addc_co_u32_e32 v127, vcc, 0, v79, vcc
	global_load_ushort v112, v[126:127], off offset:1536
	global_load_ushort v113, v[126:127], off offset:2560
	v_add_co_u32_e32 v128, vcc, 0xc000, v78
	s_nop 1
	v_addc_co_u32_e32 v129, vcc, 0, v79, vcc
	global_load_ushort v114, v[128:129], off offset:2048
	global_load_ushort v115, v[128:129], off offset:3072
	v_add_co_u32_e32 v122, vcc, 0xf000, v78
	s_nop 1
	v_addc_co_u32_e32 v123, vcc, 0, v79, vcc
	global_load_ushort v116, v[122:123], off offset:2560
	global_load_ushort v117, v[122:123], off offset:3584
	v_add_co_u32_e32 v124, vcc, 0x12000, v78
	s_nop 1
	v_addc_co_u32_e32 v125, vcc, 0, v79, vcc
	global_load_ushort v118, v[124:125], off offset:3072
	v_add_co_u32_e32 v126, vcc, 0x13000, v78
	s_nop 1
	v_addc_co_u32_e32 v127, vcc, 0, v79, vcc
	global_load_ushort v119, v[126:127], off
	v_add_co_u32_e32 v128, vcc, 0x15000, v78
	s_nop 1
	v_addc_co_u32_e32 v129, vcc, 0, v79, vcc
	global_load_ushort v120, v[128:129], off offset:3584
	v_add_co_u32_e32 v122, vcc, 0x16000, v78
	s_nop 1
	v_addc_co_u32_e32 v123, vcc, 0, v79, vcc
	global_load_ushort v121, v[122:123], off offset:512
	v_add_co_u32_e32 v78, vcc, 0x19000, v78
	s_nop 1
	v_addc_co_u32_e32 v79, vcc, 0, v79, vcc
	s_and_saveexec_b64 s[40:41], s[38:39]
	s_add_u32 s58, s44, s57
	s_addc_u32 s59, s45, s56
	v_lshl_add_u64 v[44:45], s[58:59], 0, v[38:39]
	v_mov_b32_e32 v41, v3
	v_lshl_add_u64 v[44:45], v[44:45], 0, v[40:41]
	v_add_co_u32_e32 v44, vcc, 0x3000, v44
	s_nop 1
	v_addc_co_u32_e32 v45, vcc, 0, v45, vcc
	global_load_dwordx4 v[44:47], v[44:45], off
	s_or_b64 exec, exec, s[40:41]
	s_waitcnt vmcnt(0)
	s_barrier
; #define LAS __attribute__((address_space(3)))
; __device__ __forceinline__ void ph_prep(Frame& F, int e) {
;     ...
;         for (int i = 0; i < 16; ++i) wfb[i] = (pg8::f32x2){w2[i * 512 + col], w2[(16 + i) * 512 + col]} * 1.4426950408889634f;
;         bfb = (pg8::f32x2){bg[col], bg[512 + col]} * 1.4426950408889634f;
;         __syncthreads();
;         if (F.tid < 256) { const int row = F.tid >> 2, part = F.tid & 3; const v4u w = *(const v4u*)(Prow0 + (size_t)row * DINP + C_AB + 8 * part);
;             LAS float* d = ABf + row * 32 + 16 * (part & 1) + (part >> 1);
;             d[0] = bflo(w.x); d[2] = bfhi(w.x); d[4] = bflo(w.y); d[6] = bfhi(w.y); d[8] = bflo(w.z); d[10] = bfhi(w.z); d[12] = bflo(w.w); d[14] = bfhi(w.w); }
;         __syncthreads();
;         if (!active) continue;
;         const int prw = rc & 63;
	s_and_saveexec_b64 s[40:41], s[38:39]
	s_cbranch_execz .LBB0_594
	v_lshlrev_b32_e32 v2, 16, v44
	v_and_b32_e32 v41, 0xffff0000, v44
	ds_write2_b32 v88, v2, v41 offset1:2
	v_lshlrev_b32_e32 v2, 16, v45
	v_and_b32_e32 v41, 0xffff0000, v45
	ds_write2_b32 v88, v2, v41 offset0:4 offset1:6
	v_lshlrev_b32_e32 v2, 16, v46
	v_and_b32_e32 v41, 0xffff0000, v46
	ds_write2_b32 v88, v2, v41 offset0:8 offset1:10
	v_lshlrev_b32_e32 v2, 16, v47
	v_and_b32_e32 v41, 0xffff0000, v47
	ds_write2_b32 v88, v2, v41 offset0:12 offset1:14
.LBB0_594:
	s_or_b64 exec, exec, s[40:41]
	s_or_b64 s[40:41], s[52:53], s[50:51]
	s_andn2_b64 vcc, exec, s[40:41]
	s_waitcnt lgkmcnt(0)
	s_barrier
	s_cbranch_vccnz .LBB0_591
	s_mov_b32 s30, 0x3fb8aa3b
	s_ashr_i32 s55, s54, 31
	v_pk_mul_f32 v[44:45], v[4:5], s[30:31] op_sel_hi:[1,0]
	v_pk_mul_f32 v[46:47], v[6:7], s[30:31] op_sel_hi:[1,0]
	v_pk_mul_f32 v[48:49], v[8:9], s[30:31] op_sel_hi:[1,0]
	v_pk_mul_f32 v[50:51], v[10:11], s[30:31] op_sel_hi:[1,0]
	v_pk_mul_f32 v[52:53], v[12:13], s[30:31] op_sel_hi:[1,0]
	v_pk_mul_f32 v[54:55], v[14:15], s[30:31] op_sel_hi:[1,0]
	v_pk_mul_f32 v[56:57], v[18:19], s[30:31] op_sel_hi:[1,0]
	v_pk_mul_f32 v[58:59], v[20:21], s[30:31] op_sel_hi:[1,0]
	v_pk_mul_f32 v[60:61], v[22:23], s[30:31] op_sel_hi:[1,0]
	v_pk_mul_f32 v[62:63], v[26:27], s[30:31] op_sel_hi:[1,0]
	v_pk_mul_f32 v[64:65], v[28:29], s[30:31] op_sel_hi:[1,0]
	v_pk_mul_f32 v[66:67], v[30:31], s[30:31] op_sel_hi:[1,0]
	v_pk_mul_f32 v[68:69], v[32:33], s[30:31] op_sel_hi:[1,0]
	v_pk_mul_f32 v[70:71], v[34:35], s[30:31] op_sel_hi:[1,0]
	v_pk_mul_f32 v[72:73], v[24:25], s[30:31] op_sel_hi:[1,0]
	v_pk_mul_f32 v[74:75], v[74:75], s[30:31] op_sel_hi:[1,0]
	v_pk_mul_f32 v[76:77], v[16:17], s[30:31] op_sel_hi:[1,0]
	s_and_b32 s30, s54, 63
	v_mov_b32_e32 v80, 0
	v_lshl_add_u32 v2, s54, 15, v42
	s_mov_b32 s57, 0
	s_mov_b32 s56, 0
	v_mov_b32_e32 v81, v80
	s_waitcnt vmcnt(0)
	s_branch .LBB0_597
